# in-proj epilogue for the Q_B heads rewritten by hand: QK-norm of all row groups first, rope-table rows prefetched two groups ahead with counted vmcnt waits (were 8 serialised load-wait round trips), p
# baseline (speedup 1.0000x reference)
;     DI void operator()(const AccT& acc, const Unit& u, int wr, int wc, int fr, int fq, LAS unsigned char*) const {
;         const int hh = u.pn * 4 + wc;
;         int kind, h;
;         if (hh < 8) { kind = 0; h = hh; } else if (hh < 16) { kind = 1; h = hh - 8; } else if (hh < 24) { kind = 2; h = hh - 16; }
;         else if (hh < 32) { kind = 3; h = hh - 24; } else if (hh < 34) { kind = 4; h = hh - 32; } else { kind = 5; h = hh - 34; }
;         const bool donorm = (kind != 2 && kind != 5), dorope = (kind == 3 || kind == 4);
;         const float* gain = gains + 64 * (kind == 0 ? 0 : (kind == 1 ? 1 : (kind == 3 ? 2 : 3)));
.LBB0_107:
	s_lshl_b32 s18, s6, 2
	s_or_b32 s44, s18, s69
	s_sub_i32 s0, s44, 24
	s_cmp_lt_u32 s0, 8
	s_cbranch_scc1 .Lqb_epi
	s_cmp_lt_i32 s44, 8
	s_cselect_b64 s[54:55], -1, 0
	s_and_b64 vcc, exec, s[54:55]
	s_cbranch_vccnz .LBB0_122
	s_cmp_gt_u32 s18, 15
	s_mov_b64 s[6:7], -1
	s_cbranch_scc0 .LBB0_119
	s_cmp_gt_u32 s18, 23
	s_mov_b64 s[48:49], -1
	s_cbranch_scc0 .LBB0_117
	s_cmp_gt_u32 s18, 31
	s_mov_b64 s[0:1], -1
	s_cbranch_scc0 .LBB0_115
	s_cmp_gt_u32 s44, 33
	s_cbranch_scc0 .LBB0_113
	s_sub_i32 s11, s44, 34
	s_mov_b64 s[6:7], 0

;     DI void operator()(const AccT& acc, const Unit& u, int wr, int wc, int fr, int fq, LAS unsigned char*) const {
;     ...
;         f32x4 gv[2][2];
; #pragma unroll
;         for (int bj = 0; bj < 2; ++bj)
; #pragma unroll
;             for (int n = 0; n < 2; ++n) gv[bj][n] = donorm ? *(const f32x4*)(gain + 32 * bj + 16 * n + 4 * fq) : (f32x4){1.f, 1.f, 1.f, 1.f};
; #pragma unroll
;         for (int ai = 0; ai < 2; ++ai)
; #pragma unroll
;             for (int m = 0; m < 4; ++m) {
;                 const int row = u.pm * 256 + ai * 128 + wr * 64 + m * 16 + fr;
;                 f32x4 v[2][2];
; #pragma unroll
;                 for (int bj = 0; bj < 2; ++bj)
; #pragma unroll
;                     for (int n = 0; n < 2; ++n) v[bj][n] = acc[ai][bj][m][n];
;                 if (donorm) {
;                     float ss = 0.f;
; #pragma unroll
;                     for (int bj = 0; bj < 2; ++bj)
; #pragma unroll
;                         for (int n = 0; n < 2; ++n) ss += (v[bj][n][0] * v[bj][n][0] + v[bj][n][1] * v[bj][n][1]) + (v[bj][n][2] * v[bj][n][2] + v[bj][n][3] * v[bj][n][3]);
;                     ss += __shfl_xor(ss, 16); ss += __shfl_xor(ss, 32);
;                     const float rs = rsqrtf(ss * (1.f / 64.f) + EPS);
; #pragma unroll
;                     for (int bj = 0; bj < 2; ++bj)
; #pragma unroll
;                         for (int n = 0; n < 2; ++n) v[bj][n] = v[bj][n] * rs * gv[bj][n];
;                 }
;                 if (dorope) {
;                     const int pos = row < SEQ ? row : 1024 + ((row - SEQ) & 63);
;                     const f32x4* rt = (const f32x4*)((const float*)(ws + WS_ROPE) + ((size_t)pos * 32 + 4 * fq) * 2);
; #pragma unroll
;                     for (int n = 0; n < 2; ++n) {
;                         const f32x4 t0 = rt[8 * n], t1 = rt[8 * n + 1];
;                         const float cs[4] = {t0[0], t0[2], t1[0], t1[2]}, sn[4] = {t0[1], t0[3], t1[1], t1[3]};
; #pragma unroll
;                         for (int j = 0; j < 4; ++j) { const float x1 = v[0][n][j], x2 = v[1][n][j]; v[0][n][j] = x1 * cs[j] - x2 * sn[j]; v[1][n][j] = x2 * cs[j] + x1 * sn[j]; }
;                     }
;                 }
;                 if (kind == 0 || kind == 3) {
;                     bf16_t* q = (bf16_t*)(ws + (kind == 0 ? WS_QA : WS_QB)) + ((size_t)h * MTOK + row) * 64 + 4 * fq;
; #pragma unroll
.Lqb_epi:
	global_load_dwordx4 v[200:203], v[168:169], off offset:512
	global_load_dwordx4 v[204:207], v[168:169], off offset:576
	global_load_dwordx4 v[208:211], v[168:169], off offset:640
	global_load_dwordx4 v[212:215], v[168:169], off offset:704
	v_lshl_add_u32 v216, s10, 8, v155
	s_cmp_lt_u32 s10, 64
	s_cselect_b32 s11, 0x8000, 0
	s_cselect_b64 s[6:7], -1, 0
	s_add_u32 s8, s36, 0xfa00000
	s_addc_u32 s9, s37, 0
	s_mul_i32 s18, s0, 0x240000
	s_add_u32 s46, s36, 0xc600000
	s_addc_u32 s47, s37, 0
	s_add_u32 s46, s46, s18
	s_addc_u32 s47, s47, 0
	v_lshlrev_b32_e32 v217, 7, v216
	v_cndmask_b32_e64 v216, v159, v216, s[6:7]
	v_lshl_add_u32 v217, v152, 1, v217
	v_lshlrev_b32_e32 v216, 8, v216
	v_lshl_add_u32 v216, v152, 3, v216
	s_mov_b64 s[48:49], s[8:9]
	global_load_dwordx4 v[228:231], v216, s[48:49]
	global_load_dwordx4 v[232:235], v216, s[48:49] offset:16
	global_load_dwordx4 v[236:239], v216, s[48:49] offset:128
	global_load_dwordx4 v[240:243], v216, s[48:49] offset:144
	s_add_u32 s48, s8, 0x1000
	s_addc_u32 s49, s9, 0
	global_load_dwordx4 v[244:247], v216, s[48:49]
	global_load_dwordx4 v[248:251], v216, s[48:49] offset:16
	global_load_dwordx4 v[186:189], v216, s[48:49] offset:128
	global_load_dwordx4 v[220:223], v216, s[48:49] offset:144
	s_waitcnt vmcnt(8)
	v_pk_mul_f32 v[200:201], v[200:201], s[26:27] op_sel_hi:[1,0]
	v_pk_mul_f32 v[202:203], v[202:203], s[26:27] op_sel_hi:[1,0]
	v_pk_mul_f32 v[204:205], v[204:205], s[26:27] op_sel_hi:[1,0]
	v_pk_mul_f32 v[206:207], v[206:207], s[26:27] op_sel_hi:[1,0]
	v_pk_mul_f32 v[208:209], v[208:209], s[26:27] op_sel_hi:[1,0]
	v_pk_mul_f32 v[210:211], v[210:211], s[26:27] op_sel_hi:[1,0]
	v_pk_mul_f32 v[212:213], v[212:213], s[26:27] op_sel_hi:[1,0]
	v_pk_mul_f32 v[214:215], v[214:215], s[26:27] op_sel_hi:[1,0]
	v_pk_mul_f32 v[182:183], v[128:129], v[128:129]
	v_pk_mul_f32 v[184:185], v[130:131], v[130:131]
	v_pk_fma_f32 v[182:183], v[132:133], v[132:133], v[182:183]
	v_pk_fma_f32 v[184:185], v[134:135], v[134:135], v[184:185]
	v_pk_fma_f32 v[182:183], v[136:137], v[136:137], v[182:183]
	v_pk_fma_f32 v[184:185], v[138:139], v[138:139], v[184:185]
	v_pk_fma_f32 v[182:183], v[140:141], v[140:141], v[182:183]
	v_pk_fma_f32 v[184:185], v[142:143], v[142:143], v[184:185]
	s_nop 0
	v_pk_add_f32 v[182:183], v[182:183], v[184:185]
	s_nop 0
	v_add_f32_e32 v218, v182, v183
	v_mov_b32_e32 v199, v218
	s_nop 1
	v_permlane16_swap_b32_e32 v199, v218
	v_add_f32_e32 v218, v218, v199
	v_mov_b32_e32 v199, v218
	s_nop 1
	v_permlane32_swap_b32_e32 v199, v218
	v_add_f32_e32 v218, v218, v199
	v_fmamk_f32 v218, v218, 0x3c800000, v195
	v_rsq_f32_e32 v218, v218
	s_nop 0
	v_pk_mul_f32 v[128:129], v[128:129], v[218:219] op_sel_hi:[1,0]
	v_pk_mul_f32 v[130:131], v[130:131], v[218:219] op_sel_hi:[1,0]
	v_pk_mul_f32 v[132:133], v[132:133], v[218:219] op_sel_hi:[1,0]
	v_pk_mul_f32 v[134:135], v[134:135], v[218:219] op_sel_hi:[1,0]
	v_pk_mul_f32 v[136:137], v[136:137], v[218:219] op_sel_hi:[1,0]
	v_pk_mul_f32 v[138:139], v[138:139], v[218:219] op_sel_hi:[1,0]
	v_pk_mul_f32 v[140:141], v[140:141], v[218:219] op_sel_hi:[1,0]
	v_pk_mul_f32 v[142:143], v[142:143], v[218:219] op_sel_hi:[1,0]
	v_pk_mul_f32 v[140:141], v[140:141], v[200:201]
	v_pk_mul_f32 v[142:143], v[142:143], v[202:203]
	v_pk_mul_f32 v[136:137], v[136:137], v[204:205]
	v_pk_mul_f32 v[138:139], v[138:139], v[206:207]
	v_pk_mul_f32 v[132:133], v[132:133], v[208:209]
	v_pk_mul_f32 v[134:135], v[134:135], v[210:211]
	v_pk_mul_f32 v[128:129], v[128:129], v[212:213]
	v_pk_mul_f32 v[130:131], v[130:131], v[214:215]
	v_pk_mul_f32 v[182:183], v[112:113], v[112:113]
	v_pk_mul_f32 v[184:185], v[114:115], v[114:115]
	v_pk_fma_f32 v[182:183], v[116:117], v[116:117], v[182:183]
	v_pk_fma_f32 v[184:185], v[118:119], v[118:119], v[184:185]
	v_pk_fma_f32 v[182:183], v[120:121], v[120:121], v[182:183]
	v_pk_fma_f32 v[184:185], v[122:123], v[122:123], v[184:185]
	v_pk_fma_f32 v[182:183], v[124:125], v[124:125], v[182:183]
	v_pk_fma_f32 v[184:185], v[126:127], v[126:127], v[184:185]
	s_nop 0
	v_pk_add_f32 v[182:183], v[182:183], v[184:185]
	s_nop 0
	v_add_f32_e32 v218, v182, v183
	v_mov_b32_e32 v199, v218
	s_nop 1
	v_permlane16_swap_b32_e32 v199, v218
	v_add_f32_e32 v218, v218, v199
	v_mov_b32_e32 v199, v218
	s_nop 1
	v_permlane32_swap_b32_e32 v199, v218
	v_add_f32_e32 v218, v218, v199
	v_fmamk_f32 v218, v218, 0x3c800000, v195
	v_rsq_f32_e32 v218, v218
	s_nop 0
	v_pk_mul_f32 v[112:113], v[112:113], v[218:219] op_sel_hi:[1,0]
	v_pk_mul_f32 v[114:115], v[114:115], v[218:219] op_sel_hi:[1,0]
	v_pk_mul_f32 v[116:117], v[116:117], v[218:219] op_sel_hi:[1,0]
	v_pk_mul_f32 v[118:119], v[118:119], v[218:219] op_sel_hi:[1,0]
	v_pk_mul_f32 v[120:121], v[120:121], v[218:219] op_sel_hi:[1,0]
	v_pk_mul_f32 v[122:123], v[122:123], v[218:219] op_sel_hi:[1,0]
	v_pk_mul_f32 v[124:125], v[124:125], v[218:219] op_sel_hi:[1,0]
	v_pk_mul_f32 v[126:127], v[126:127], v[218:219] op_sel_hi:[1,0]
	v_pk_mul_f32 v[124:125], v[124:125], v[200:201]
	v_pk_mul_f32 v[126:127], v[126:127], v[202:203]
	v_pk_mul_f32 v[120:121], v[120:121], v[204:205]
	v_pk_mul_f32 v[122:123], v[122:123], v[206:207]
	v_pk_mul_f32 v[116:117], v[116:117], v[208:209]
	v_pk_mul_f32 v[118:119], v[118:119], v[210:211]
	v_pk_mul_f32 v[112:113], v[112:113], v[212:213]
	v_pk_mul_f32 v[114:115], v[114:115], v[214:215]
	v_pk_mul_f32 v[182:183], v[96:97], v[96:97]
	v_pk_mul_f32 v[184:185], v[98:99], v[98:99]
	v_pk_fma_f32 v[182:183], v[100:101], v[100:101], v[182:183]
	v_pk_fma_f32 v[184:185], v[102:103], v[102:103], v[184:185]
	v_pk_fma_f32 v[182:183], v[104:105], v[104:105], v[182:183]
	v_pk_fma_f32 v[184:185], v[106:107], v[106:107], v[184:185]
;     DI void operator()(const AccT& acc, const Unit& u, int wr, int wc, int fr, int fq, LAS unsigned char*) const {
;     ...
;                 if (donorm) {
;                     float ss = 0.f;
; #pragma unroll
;                     for (int bj = 0; bj < 2; ++bj)
; #pragma unroll
;                         for (int n = 0; n < 2; ++n) ss += (v[bj][n][0] * v[bj][n][0] + v[bj][n][1] * v[bj][n][1]) + (v[bj][n][2] * v[bj][n][2] + v[bj][n][3] * v[bj][n][3]);
;                     ss += __shfl_xor(ss, 16); ss += __shfl_xor(ss, 32);
;                     const float rs = rsqrtf(ss * (1.f / 64.f) + EPS);
; #pragma unroll
;                     for (int bj = 0; bj < 2; ++bj)
; #pragma unroll
;                         for (int n = 0; n < 2; ++n) v[bj][n] = v[bj][n] * rs * gv[bj][n];
;                 }
	v_pk_fma_f32 v[182:183], v[108:109], v[108:109], v[182:183]
	v_pk_fma_f32 v[184:185], v[110:111], v[110:111], v[184:185]
	s_nop 0
	v_pk_add_f32 v[182:183], v[182:183], v[184:185]
	s_nop 0
	v_add_f32_e32 v218, v182, v183
	v_mov_b32_e32 v199, v218
	s_nop 1
	v_permlane16_swap_b32_e32 v199, v218
	v_add_f32_e32 v218, v218, v199
	v_mov_b32_e32 v199, v218
	s_nop 1
	v_permlane32_swap_b32_e32 v199, v218
	v_add_f32_e32 v218, v218, v199
	v_fmamk_f32 v218, v218, 0x3c800000, v195
	v_rsq_f32_e32 v218, v218
	s_nop 0
	v_pk_mul_f32 v[96:97], v[96:97], v[218:219] op_sel_hi:[1,0]
	v_pk_mul_f32 v[98:99], v[98:99], v[218:219] op_sel_hi:[1,0]
	v_pk_mul_f32 v[100:101], v[100:101], v[218:219] op_sel_hi:[1,0]
	v_pk_mul_f32 v[102:103], v[102:103], v[218:219] op_sel_hi:[1,0]
	v_pk_mul_f32 v[104:105], v[104:105], v[218:219] op_sel_hi:[1,0]
	v_pk_mul_f32 v[106:107], v[106:107], v[218:219] op_sel_hi:[1,0]
	v_pk_mul_f32 v[108:109], v[108:109], v[218:219] op_sel_hi:[1,0]
	v_pk_mul_f32 v[110:111], v[110:111], v[218:219] op_sel_hi:[1,0]
	v_pk_mul_f32 v[108:109], v[108:109], v[200:201]
	v_pk_mul_f32 v[110:111], v[110:111], v[202:203]
	v_pk_mul_f32 v[104:105], v[104:105], v[204:205]
	v_pk_mul_f32 v[106:107], v[106:107], v[206:207]
	v_pk_mul_f32 v[100:101], v[100:101], v[208:209]
	v_pk_mul_f32 v[102:103], v[102:103], v[210:211]
	v_pk_mul_f32 v[96:97], v[96:97], v[212:213]
	v_pk_mul_f32 v[98:99], v[98:99], v[214:215]
	v_pk_mul_f32 v[182:183], v[80:81], v[80:81]
	v_pk_mul_f32 v[184:185], v[82:83], v[82:83]
	v_pk_fma_f32 v[182:183], v[84:85], v[84:85], v[182:183]
	v_pk_fma_f32 v[184:185], v[86:87], v[86:87], v[184:185]
	v_pk_fma_f32 v[182:183], v[88:89], v[88:89], v[182:183]
	v_pk_fma_f32 v[184:185], v[90:91], v[90:91], v[184:185]
	v_pk_fma_f32 v[182:183], v[92:93], v[92:93], v[182:183]
	v_pk_fma_f32 v[184:185], v[94:95], v[94:95], v[184:185]
	s_nop 0
	v_pk_add_f32 v[182:183], v[182:183], v[184:185]
	s_nop 0
	v_add_f32_e32 v218, v182, v183
	v_mov_b32_e32 v199, v218
	s_nop 1
	v_permlane16_swap_b32_e32 v199, v218
	v_add_f32_e32 v218, v218, v199
	v_mov_b32_e32 v199, v218
	s_nop 1
	v_permlane32_swap_b32_e32 v199, v218
	v_add_f32_e32 v218, v218, v199
	v_fmamk_f32 v218, v218, 0x3c800000, v195
	v_rsq_f32_e32 v218, v218
	s_nop 0
	v_pk_mul_f32 v[80:81], v[80:81], v[218:219] op_sel_hi:[1,0]
	v_pk_mul_f32 v[82:83], v[82:83], v[218:219] op_sel_hi:[1,0]
	v_pk_mul_f32 v[84:85], v[84:85], v[218:219] op_sel_hi:[1,0]
	v_pk_mul_f32 v[86:87], v[86:87], v[218:219] op_sel_hi:[1,0]
	v_pk_mul_f32 v[88:89], v[88:89], v[218:219] op_sel_hi:[1,0]
	v_pk_mul_f32 v[90:91], v[90:91], v[218:219] op_sel_hi:[1,0]
	v_pk_mul_f32 v[92:93], v[92:93], v[218:219] op_sel_hi:[1,0]
	v_pk_mul_f32 v[94:95], v[94:95], v[218:219] op_sel_hi:[1,0]
	v_pk_mul_f32 v[92:93], v[92:93], v[200:201]
	v_pk_mul_f32 v[94:95], v[94:95], v[202:203]
	v_pk_mul_f32 v[88:89], v[88:89], v[204:205]
	v_pk_mul_f32 v[90:91], v[90:91], v[206:207]
	v_pk_mul_f32 v[84:85], v[84:85], v[208:209]
	v_pk_mul_f32 v[86:87], v[86:87], v[210:211]
	v_pk_mul_f32 v[80:81], v[80:81], v[212:213]
	v_pk_mul_f32 v[82:83], v[82:83], v[214:215]
	v_pk_mul_f32 v[182:183], v[64:65], v[64:65]
	v_pk_mul_f32 v[184:185], v[66:67], v[66:67]
	v_pk_fma_f32 v[182:183], v[68:69], v[68:69], v[182:183]
	v_pk_fma_f32 v[184:185], v[70:71], v[70:71], v[184:185]
	v_pk_fma_f32 v[182:183], v[72:73], v[72:73], v[182:183]
	v_pk_fma_f32 v[184:185], v[74:75], v[74:75], v[184:185]
	v_pk_fma_f32 v[182:183], v[76:77], v[76:77], v[182:183]
	v_pk_fma_f32 v[184:185], v[78:79], v[78:79], v[184:185]
	s_nop 0
	v_pk_add_f32 v[182:183], v[182:183], v[184:185]
	s_nop 0
	v_add_f32_e32 v218, v182, v183
	v_mov_b32_e32 v199, v218
	s_nop 1
	v_permlane16_swap_b32_e32 v199, v218
	v_add_f32_e32 v218, v218, v199
	v_mov_b32_e32 v199, v218
	s_nop 1
	v_permlane32_swap_b32_e32 v199, v218
	v_add_f32_e32 v218, v218, v199
	v_fmamk_f32 v218, v218, 0x3c800000, v195
	v_rsq_f32_e32 v218, v218
	s_nop 0
	v_pk_mul_f32 v[64:65], v[64:65], v[218:219] op_sel_hi:[1,0]
	v_pk_mul_f32 v[66:67], v[66:67], v[218:219] op_sel_hi:[1,0]
	v_pk_mul_f32 v[68:69], v[68:69], v[218:219] op_sel_hi:[1,0]
	v_pk_mul_f32 v[70:71], v[70:71], v[218:219] op_sel_hi:[1,0]
	v_pk_mul_f32 v[72:73], v[72:73], v[218:219] op_sel_hi:[1,0]
	v_pk_mul_f32 v[74:75], v[74:75], v[218:219] op_sel_hi:[1,0]
	v_pk_mul_f32 v[76:77], v[76:77], v[218:219] op_sel_hi:[1,0]
	v_pk_mul_f32 v[78:79], v[78:79], v[218:219] op_sel_hi:[1,0]
	v_pk_mul_f32 v[76:77], v[76:77], v[200:201]
	v_pk_mul_f32 v[78:79], v[78:79], v[202:203]
	v_pk_mul_f32 v[72:73], v[72:73], v[204:205]
	v_pk_mul_f32 v[74:75], v[74:75], v[206:207]
	v_pk_mul_f32 v[68:69], v[68:69], v[208:209]
	v_pk_mul_f32 v[70:71], v[70:71], v[210:211]
	v_pk_mul_f32 v[64:65], v[64:65], v[212:213]
	v_pk_mul_f32 v[66:67], v[66:67], v[214:215]
	v_pk_mul_f32 v[182:183], v[32:33], v[32:33]
	v_pk_mul_f32 v[184:185], v[34:35], v[34:35]
	v_pk_fma_f32 v[182:183], v[36:37], v[36:37], v[182:183]
	v_pk_fma_f32 v[184:185], v[38:39], v[38:39], v[184:185]
	v_pk_fma_f32 v[182:183], v[40:41], v[40:41], v[182:183]
	v_pk_fma_f32 v[184:185], v[42:43], v[42:43], v[184:185]
	v_pk_fma_f32 v[182:183], v[44:45], v[44:45], v[182:183]
	v_pk_fma_f32 v[184:185], v[46:47], v[46:47], v[184:185]
	s_nop 0
	v_pk_add_f32 v[182:183], v[182:183], v[184:185]
	s_nop 0
	v_add_f32_e32 v218, v182, v183
	v_mov_b32_e32 v199, v218
	s_nop 1
	v_permlane16_swap_b32_e32 v199, v218
	v_add_f32_e32 v218, v218, v199
	v_mov_b32_e32 v199, v218
	s_nop 1
	v_permlane32_swap_b32_e32 v199, v218
	v_add_f32_e32 v218, v218, v199
	v_fmamk_f32 v218, v218, 0x3c800000, v195
	v_rsq_f32_e32 v218, v218
	s_nop 0
	v_pk_mul_f32 v[32:33], v[32:33], v[218:219] op_sel_hi:[1,0]
; DI u32x2 pk4(f32x4 v) { u32x2 r; r.x = pk2(v[0], v[1]); r.y = pk2(v[2], v[3]); return r; }
;     DI void operator()(const AccT& acc, const Unit& u, int wr, int wc, int fr, int fq, LAS unsigned char*) const {
;     ...
;                 if (donorm) {
;                     float ss = 0.f;
; #pragma unroll
;                     for (int bj = 0; bj < 2; ++bj)
; #pragma unroll
;                         for (int n = 0; n < 2; ++n) ss += (v[bj][n][0] * v[bj][n][0] + v[bj][n][1] * v[bj][n][1]) + (v[bj][n][2] * v[bj][n][2] + v[bj][n][3] * v[bj][n][3]);
;                     ss += __shfl_xor(ss, 16); ss += __shfl_xor(ss, 32);
;                     const float rs = rsqrtf(ss * (1.f / 64.f) + EPS);
; #pragma unroll
;                     for (int bj = 0; bj < 2; ++bj)
; #pragma unroll
;                         for (int n = 0; n < 2; ++n) v[bj][n] = v[bj][n] * rs * gv[bj][n];
;                 }
;                 if (dorope) {
;                     const int pos = row < SEQ ? row : 1024 + ((row - SEQ) & 63);
;                     const f32x4* rt = (const f32x4*)((const float*)(ws + WS_ROPE) + ((size_t)pos * 32 + 4 * fq) * 2);
; #pragma unroll
;                     for (int n = 0; n < 2; ++n) {
;                         const f32x4 t0 = rt[8 * n], t1 = rt[8 * n + 1];
;                         const float cs[4] = {t0[0], t0[2], t1[0], t1[2]}, sn[4] = {t0[1], t0[3], t1[1], t1[3]};
; #pragma unroll
;                         for (int j = 0; j < 4; ++j) { const float x1 = v[0][n][j], x2 = v[1][n][j]; v[0][n][j] = x1 * cs[j] - x2 * sn[j]; v[1][n][j] = x2 * cs[j] + x1 * sn[j]; }
;                     }
;                 }
;                 if (kind == 0 || kind == 3) {
;                     bf16_t* q = (bf16_t*)(ws + (kind == 0 ? WS_QA : WS_QB)) + ((size_t)h * MTOK + row) * 64 + 4 * fq;
; #pragma unroll
;                     for (int bj = 0; bj < 2; ++bj)
; #pragma unroll
;                         for (int n = 0; n < 2; ++n) *(u32x2*)(q + 32 * bj + 16 * n) = pk4(v[bj][n] * QSCALE);
	v_pk_mul_f32 v[34:35], v[34:35], v[218:219] op_sel_hi:[1,0]
	v_pk_mul_f32 v[36:37], v[36:37], v[218:219] op_sel_hi:[1,0]
	v_pk_mul_f32 v[38:39], v[38:39], v[218:219] op_sel_hi:[1,0]
	v_pk_mul_f32 v[40:41], v[40:41], v[218:219] op_sel_hi:[1,0]
	v_pk_mul_f32 v[42:43], v[42:43], v[218:219] op_sel_hi:[1,0]
	v_pk_mul_f32 v[44:45], v[44:45], v[218:219] op_sel_hi:[1,0]
	v_pk_mul_f32 v[46:47], v[46:47], v[218:219] op_sel_hi:[1,0]
	v_pk_mul_f32 v[44:45], v[44:45], v[200:201]
	v_pk_mul_f32 v[46:47], v[46:47], v[202:203]
	v_pk_mul_f32 v[40:41], v[40:41], v[204:205]
	v_pk_mul_f32 v[42:43], v[42:43], v[206:207]
	v_pk_mul_f32 v[36:37], v[36:37], v[208:209]
	v_pk_mul_f32 v[38:39], v[38:39], v[210:211]
	v_pk_mul_f32 v[32:33], v[32:33], v[212:213]
	v_pk_mul_f32 v[34:35], v[34:35], v[214:215]
	v_pk_mul_f32 v[182:183], v[16:17], v[16:17]
	v_pk_mul_f32 v[184:185], v[18:19], v[18:19]
	v_pk_fma_f32 v[182:183], v[20:21], v[20:21], v[182:183]
	v_pk_fma_f32 v[184:185], v[22:23], v[22:23], v[184:185]
	v_pk_fma_f32 v[182:183], v[24:25], v[24:25], v[182:183]
	v_pk_fma_f32 v[184:185], v[26:27], v[26:27], v[184:185]
	v_pk_fma_f32 v[182:183], v[28:29], v[28:29], v[182:183]
	v_pk_fma_f32 v[184:185], v[30:31], v[30:31], v[184:185]
	s_nop 0
	v_pk_add_f32 v[182:183], v[182:183], v[184:185]
	s_nop 0
	v_add_f32_e32 v218, v182, v183
	v_mov_b32_e32 v199, v218
	s_nop 1
	v_permlane16_swap_b32_e32 v199, v218
	v_add_f32_e32 v218, v218, v199
	v_mov_b32_e32 v199, v218
	s_nop 1
	v_permlane32_swap_b32_e32 v199, v218
	v_add_f32_e32 v218, v218, v199
	v_fmamk_f32 v218, v218, 0x3c800000, v195
	v_rsq_f32_e32 v218, v218
	s_nop 0
	v_pk_mul_f32 v[16:17], v[16:17], v[218:219] op_sel_hi:[1,0]
	v_pk_mul_f32 v[18:19], v[18:19], v[218:219] op_sel_hi:[1,0]
	v_pk_mul_f32 v[20:21], v[20:21], v[218:219] op_sel_hi:[1,0]
	v_pk_mul_f32 v[22:23], v[22:23], v[218:219] op_sel_hi:[1,0]
	v_pk_mul_f32 v[24:25], v[24:25], v[218:219] op_sel_hi:[1,0]
	v_pk_mul_f32 v[26:27], v[26:27], v[218:219] op_sel_hi:[1,0]
	v_pk_mul_f32 v[28:29], v[28:29], v[218:219] op_sel_hi:[1,0]
	v_pk_mul_f32 v[30:31], v[30:31], v[218:219] op_sel_hi:[1,0]
	v_pk_mul_f32 v[28:29], v[28:29], v[200:201]
	v_pk_mul_f32 v[30:31], v[30:31], v[202:203]
	v_pk_mul_f32 v[24:25], v[24:25], v[204:205]
	v_pk_mul_f32 v[26:27], v[26:27], v[206:207]
	v_pk_mul_f32 v[20:21], v[20:21], v[208:209]
	v_pk_mul_f32 v[22:23], v[22:23], v[210:211]
	v_pk_mul_f32 v[16:17], v[16:17], v[212:213]
	v_pk_mul_f32 v[18:19], v[18:19], v[214:215]
	v_pk_mul_f32 v[182:183], v[0:1], v[0:1]
	v_pk_mul_f32 v[184:185], v[2:3], v[2:3]
	v_pk_fma_f32 v[182:183], v[4:5], v[4:5], v[182:183]
	v_pk_fma_f32 v[184:185], v[6:7], v[6:7], v[184:185]
	v_pk_fma_f32 v[182:183], v[8:9], v[8:9], v[182:183]
	v_pk_fma_f32 v[184:185], v[10:11], v[10:11], v[184:185]
	v_pk_fma_f32 v[182:183], v[12:13], v[12:13], v[182:183]
	v_pk_fma_f32 v[184:185], v[14:15], v[14:15], v[184:185]
	s_nop 0
	v_pk_add_f32 v[182:183], v[182:183], v[184:185]
	s_nop 0
	v_add_f32_e32 v218, v182, v183
	v_mov_b32_e32 v199, v218
	s_nop 1
	v_permlane16_swap_b32_e32 v199, v218
	v_add_f32_e32 v218, v218, v199
	v_mov_b32_e32 v199, v218
	s_nop 1
	v_permlane32_swap_b32_e32 v199, v218
	v_add_f32_e32 v218, v218, v199
	v_fmamk_f32 v218, v218, 0x3c800000, v195
	v_rsq_f32_e32 v218, v218
	s_nop 0
	v_pk_mul_f32 v[0:1], v[0:1], v[218:219] op_sel_hi:[1,0]
	v_pk_mul_f32 v[2:3], v[2:3], v[218:219] op_sel_hi:[1,0]
	v_pk_mul_f32 v[4:5], v[4:5], v[218:219] op_sel_hi:[1,0]
	v_pk_mul_f32 v[6:7], v[6:7], v[218:219] op_sel_hi:[1,0]
	v_pk_mul_f32 v[8:9], v[8:9], v[218:219] op_sel_hi:[1,0]
	v_pk_mul_f32 v[10:11], v[10:11], v[218:219] op_sel_hi:[1,0]
	v_pk_mul_f32 v[12:13], v[12:13], v[218:219] op_sel_hi:[1,0]
	v_pk_mul_f32 v[14:15], v[14:15], v[218:219] op_sel_hi:[1,0]
	v_pk_mul_f32 v[12:13], v[12:13], v[200:201]
	v_pk_mul_f32 v[14:15], v[14:15], v[202:203]
	v_pk_mul_f32 v[8:9], v[8:9], v[204:205]
	v_pk_mul_f32 v[10:11], v[10:11], v[206:207]
	v_pk_mul_f32 v[4:5], v[4:5], v[208:209]
	v_pk_mul_f32 v[6:7], v[6:7], v[210:211]
	v_pk_mul_f32 v[0:1], v[0:1], v[212:213]
	v_pk_mul_f32 v[2:3], v[2:3], v[214:215]
	s_waitcnt vmcnt(4)
	v_pk_mul_f32 v[184:185], v[140:141], v[228:229] op_sel:[0,0] op_sel_hi:[0,1]
	v_pk_mul_f32 v[182:183], v[140:141], v[230:231] op_sel:[1,0] op_sel_hi:[1,1]
	v_pk_fma_f32 v[228:229], v[132:133], v[228:229], v[184:185] op_sel:[0,1,0] op_sel_hi:[0,0,1] neg_lo:[0,1,0]
	v_pk_fma_f32 v[230:231], v[132:133], v[230:231], v[182:183] op_sel:[1,1,0] op_sel_hi:[1,0,1] neg_lo:[0,1,0]
	v_pk_mul_f32 v[184:185], v[142:143], v[232:233] op_sel:[0,0] op_sel_hi:[0,1]
	v_pk_mul_f32 v[182:183], v[142:143], v[234:235] op_sel:[1,0] op_sel_hi:[1,1]
	v_pk_fma_f32 v[232:233], v[134:135], v[232:233], v[184:185] op_sel:[0,1,0] op_sel_hi:[0,0,1] neg_lo:[0,1,0]
	v_pk_fma_f32 v[234:235], v[134:135], v[234:235], v[182:183] op_sel:[1,1,0] op_sel_hi:[1,0,1] neg_lo:[0,1,0]
	v_pk_mul_f32 v[184:185], v[136:137], v[236:237] op_sel:[0,0] op_sel_hi:[0,1]
	v_pk_mul_f32 v[182:183], v[136:137], v[238:239] op_sel:[1,0] op_sel_hi:[1,1]
	v_pk_fma_f32 v[236:237], v[128:129], v[236:237], v[184:185] op_sel:[0,1,0] op_sel_hi:[0,0,1] neg_lo:[0,1,0]
	v_pk_fma_f32 v[238:239], v[128:129], v[238:239], v[182:183] op_sel:[1,1,0] op_sel_hi:[1,0,1] neg_lo:[0,1,0]
	v_pk_mul_f32 v[184:185], v[138:139], v[240:241] op_sel:[0,0] op_sel_hi:[0,1]
	v_pk_mul_f32 v[182:183], v[138:139], v[242:243] op_sel:[1,0] op_sel_hi:[1,1]
	v_pk_fma_f32 v[240:241], v[130:131], v[240:241], v[184:185] op_sel:[0,1,0] op_sel_hi:[0,0,1] neg_lo:[0,1,0]
	v_pk_fma_f32 v[242:243], v[130:131], v[242:243], v[182:183] op_sel:[1,1,0] op_sel_hi:[1,0,1] neg_lo:[0,1,0]
	v_cvt_pk_bf16_f32 v140, v228, v230
	v_cvt_pk_bf16_f32 v141, v232, v234
	v_cvt_pk_bf16_f32 v132, v229, v231
	v_cvt_pk_bf16_f32 v133, v233, v235
	v_cvt_pk_bf16_f32 v136, v236, v238
	v_cvt_pk_bf16_f32 v137, v240, v242
	v_cvt_pk_bf16_f32 v128, v237, v239
	v_cvt_pk_bf16_f32 v129, v241, v243
	global_store_dwordx2 v217, v[140:141], s[46:47]
	global_store_dwordx2 v217, v[136:137], s[46:47] offset:32
	global_store_dwordx2 v217, v[132:133], s[46:47] offset:64
	global_store_dwordx2 v217, v[128:129], s[46:47] offset:96
	s_add_u32 s48, s8, 0x2000
	s_addc_u32 s49, s9, 0
	global_load_dwordx4 v[228:231], v216, s[48:49]
	global_load_dwordx4 v[232:235], v216, s[48:49] offset:16
	global_load_dwordx4 v[236:239], v216, s[48:49] offset:128
	global_load_dwordx4 v[240:243], v216, s[48:49] offset:144
	s_nop 0
	s_add_u32 s48, s8, 0x3000
	s_addc_u32 s49, s9, 0
	global_load_dwordx4 v[140:143], v216, s[48:49]
	global_load_dwordx4 v[136:139], v216, s[48:49] offset:16
	global_load_dwordx4 v[132:135], v216, s[48:49] offset:128
	global_load_dwordx4 v[128:131], v216, s[48:49] offset:144
	s_waitcnt vmcnt(12)
; DI u32x2 pk4(f32x4 v) { u32x2 r; r.x = pk2(v[0], v[1]); r.y = pk2(v[2], v[3]); return r; }
;     DI void operator()(const AccT& acc, const Unit& u, int wr, int wc, int fr, int fq, LAS unsigned char*) const {
;     ...
;                 if (dorope) {
;                     const int pos = row < SEQ ? row : 1024 + ((row - SEQ) & 63);
;                     const f32x4* rt = (const f32x4*)((const float*)(ws + WS_ROPE) + ((size_t)pos * 32 + 4 * fq) * 2);
; #pragma unroll
;                     for (int n = 0; n < 2; ++n) {
;                         const f32x4 t0 = rt[8 * n], t1 = rt[8 * n + 1];
;                         const float cs[4] = {t0[0], t0[2], t1[0], t1[2]}, sn[4] = {t0[1], t0[3], t1[1], t1[3]};
; #pragma unroll
;                         for (int j = 0; j < 4; ++j) { const float x1 = v[0][n][j], x2 = v[1][n][j]; v[0][n][j] = x1 * cs[j] - x2 * sn[j]; v[1][n][j] = x2 * cs[j] + x1 * sn[j]; }
;                     }
;                 }
;                 if (kind == 0 || kind == 3) {
;                     bf16_t* q = (bf16_t*)(ws + (kind == 0 ? WS_QA : WS_QB)) + ((size_t)h * MTOK + row) * 64 + 4 * fq;
; #pragma unroll
;                     for (int bj = 0; bj < 2; ++bj)
; #pragma unroll
;                         for (int n = 0; n < 2; ++n) *(u32x2*)(q + 32 * bj + 16 * n) = pk4(v[bj][n] * QSCALE);
	v_pk_mul_f32 v[184:185], v[124:125], v[244:245] op_sel:[0,0] op_sel_hi:[0,1]
	v_pk_mul_f32 v[182:183], v[124:125], v[246:247] op_sel:[1,0] op_sel_hi:[1,1]
	v_pk_fma_f32 v[244:245], v[116:117], v[244:245], v[184:185] op_sel:[0,1,0] op_sel_hi:[0,0,1] neg_lo:[0,1,0]
	v_pk_fma_f32 v[246:247], v[116:117], v[246:247], v[182:183] op_sel:[1,1,0] op_sel_hi:[1,0,1] neg_lo:[0,1,0]
	v_pk_mul_f32 v[184:185], v[126:127], v[248:249] op_sel:[0,0] op_sel_hi:[0,1]
	v_pk_mul_f32 v[182:183], v[126:127], v[250:251] op_sel:[1,0] op_sel_hi:[1,1]
	v_pk_fma_f32 v[248:249], v[118:119], v[248:249], v[184:185] op_sel:[0,1,0] op_sel_hi:[0,0,1] neg_lo:[0,1,0]
	v_pk_fma_f32 v[250:251], v[118:119], v[250:251], v[182:183] op_sel:[1,1,0] op_sel_hi:[1,0,1] neg_lo:[0,1,0]
	v_pk_mul_f32 v[184:185], v[120:121], v[186:187] op_sel:[0,0] op_sel_hi:[0,1]
	v_pk_mul_f32 v[182:183], v[120:121], v[188:189] op_sel:[1,0] op_sel_hi:[1,1]
	v_pk_fma_f32 v[186:187], v[112:113], v[186:187], v[184:185] op_sel:[0,1,0] op_sel_hi:[0,0,1] neg_lo:[0,1,0]
	v_pk_fma_f32 v[188:189], v[112:113], v[188:189], v[182:183] op_sel:[1,1,0] op_sel_hi:[1,0,1] neg_lo:[0,1,0]
	v_pk_mul_f32 v[184:185], v[122:123], v[220:221] op_sel:[0,0] op_sel_hi:[0,1]
	v_pk_mul_f32 v[182:183], v[122:123], v[222:223] op_sel:[1,0] op_sel_hi:[1,1]
	v_pk_fma_f32 v[220:221], v[114:115], v[220:221], v[184:185] op_sel:[0,1,0] op_sel_hi:[0,0,1] neg_lo:[0,1,0]
	v_pk_fma_f32 v[222:223], v[114:115], v[222:223], v[182:183] op_sel:[1,1,0] op_sel_hi:[1,0,1] neg_lo:[0,1,0]
	v_cvt_pk_bf16_f32 v124, v244, v246
	v_cvt_pk_bf16_f32 v125, v248, v250
	v_cvt_pk_bf16_f32 v116, v245, v247
	v_cvt_pk_bf16_f32 v117, v249, v251
	v_cvt_pk_bf16_f32 v120, v186, v188
	v_cvt_pk_bf16_f32 v121, v220, v222
	v_cvt_pk_bf16_f32 v112, v187, v189
	v_cvt_pk_bf16_f32 v113, v221, v223
	s_add_u32 s50, s46, 0x800
	s_addc_u32 s51, s47, 0
	global_store_dwordx2 v217, v[124:125], s[50:51]
	global_store_dwordx2 v217, v[120:121], s[50:51] offset:32
	global_store_dwordx2 v217, v[116:117], s[50:51] offset:64
	global_store_dwordx2 v217, v[112:113], s[50:51] offset:96
	s_mov_b64 s[48:49], s[8:9]
	s_add_u32 s48, s48, s11
	s_addc_u32 s49, s49, 0
	global_load_dwordx4 v[244:247], v216, s[48:49]
	global_load_dwordx4 v[248:251], v216, s[48:49] offset:16
	global_load_dwordx4 v[186:189], v216, s[48:49] offset:128
	global_load_dwordx4 v[220:223], v216, s[48:49] offset:144
	s_nop 0
	s_add_u32 s48, s8, 0x1000
	s_addc_u32 s49, s9, 0
	s_add_u32 s48, s48, s11
	s_addc_u32 s49, s49, 0
	global_load_dwordx4 v[124:127], v216, s[48:49]
	global_load_dwordx4 v[120:123], v216, s[48:49] offset:16
	global_load_dwordx4 v[116:119], v216, s[48:49] offset:128
	global_load_dwordx4 v[112:115], v216, s[48:49] offset:144
	s_waitcnt vmcnt(16)
	v_pk_mul_f32 v[184:185], v[108:109], v[228:229] op_sel:[0,0] op_sel_hi:[0,1]
	v_pk_mul_f32 v[182:183], v[108:109], v[230:231] op_sel:[1,0] op_sel_hi:[1,1]
	v_pk_fma_f32 v[228:229], v[100:101], v[228:229], v[184:185] op_sel:[0,1,0] op_sel_hi:[0,0,1] neg_lo:[0,1,0]
	v_pk_fma_f32 v[230:231], v[100:101], v[230:231], v[182:183] op_sel:[1,1,0] op_sel_hi:[1,0,1] neg_lo:[0,1,0]
	v_pk_mul_f32 v[184:185], v[110:111], v[232:233] op_sel:[0,0] op_sel_hi:[0,1]
	v_pk_mul_f32 v[182:183], v[110:111], v[234:235] op_sel:[1,0] op_sel_hi:[1,1]
	v_pk_fma_f32 v[232:233], v[102:103], v[232:233], v[184:185] op_sel:[0,1,0] op_sel_hi:[0,0,1] neg_lo:[0,1,0]
	v_pk_fma_f32 v[234:235], v[102:103], v[234:235], v[182:183] op_sel:[1,1,0] op_sel_hi:[1,0,1] neg_lo:[0,1,0]
	v_pk_mul_f32 v[184:185], v[104:105], v[236:237] op_sel:[0,0] op_sel_hi:[0,1]
	v_pk_mul_f32 v[182:183], v[104:105], v[238:239] op_sel:[1,0] op_sel_hi:[1,1]
	v_pk_fma_f32 v[236:237], v[96:97], v[236:237], v[184:185] op_sel:[0,1,0] op_sel_hi:[0,0,1] neg_lo:[0,1,0]
	v_pk_fma_f32 v[238:239], v[96:97], v[238:239], v[182:183] op_sel:[1,1,0] op_sel_hi:[1,0,1] neg_lo:[0,1,0]
	v_pk_mul_f32 v[184:185], v[106:107], v[240:241] op_sel:[0,0] op_sel_hi:[0,1]
	v_pk_mul_f32 v[182:183], v[106:107], v[242:243] op_sel:[1,0] op_sel_hi:[1,1]
	v_pk_fma_f32 v[240:241], v[98:99], v[240:241], v[184:185] op_sel:[0,1,0] op_sel_hi:[0,0,1] neg_lo:[0,1,0]
	v_pk_fma_f32 v[242:243], v[98:99], v[242:243], v[182:183] op_sel:[1,1,0] op_sel_hi:[1,0,1] neg_lo:[0,1,0]
	v_cvt_pk_bf16_f32 v108, v228, v230
	v_cvt_pk_bf16_f32 v109, v232, v234
	v_cvt_pk_bf16_f32 v100, v229, v231
	v_cvt_pk_bf16_f32 v101, v233, v235
	v_cvt_pk_bf16_f32 v104, v236, v238
	v_cvt_pk_bf16_f32 v105, v240, v242
	v_cvt_pk_bf16_f32 v96, v237, v239
	v_cvt_pk_bf16_f32 v97, v241, v243
	s_add_u32 s50, s46, 0x1000
	s_addc_u32 s51, s47, 0
	global_store_dwordx2 v217, v[108:109], s[50:51]
	global_store_dwordx2 v217, v[104:105], s[50:51] offset:32
	global_store_dwordx2 v217, v[100:101], s[50:51] offset:64
	global_store_dwordx2 v217, v[96:97], s[50:51] offset:96
	s_add_u32 s48, s8, 0x2000
	s_addc_u32 s49, s9, 0
	s_add_u32 s48, s48, s11
	s_addc_u32 s49, s49, 0
	global_load_dwordx4 v[228:231], v216, s[48:49]
	global_load_dwordx4 v[232:235], v216, s[48:49] offset:16
	global_load_dwordx4 v[236:239], v216, s[48:49] offset:128
	global_load_dwordx4 v[240:243], v216, s[48:49] offset:144
	s_nop 0
	s_add_u32 s48, s8, 0x3000
	s_addc_u32 s49, s9, 0
	s_add_u32 s48, s48, s11
	s_addc_u32 s49, s49, 0
	global_load_dwordx4 v[108:111], v216, s[48:49]
	global_load_dwordx4 v[104:107], v216, s[48:49] offset:16
	global_load_dwordx4 v[100:103], v216, s[48:49] offset:128
	global_load_dwordx4 v[96:99], v216, s[48:49] offset:144
	s_waitcnt vmcnt(24)
; DI u32x2 pk4(f32x4 v) { u32x2 r; r.x = pk2(v[0], v[1]); r.y = pk2(v[2], v[3]); return r; }
;     DI void operator()(const AccT& acc, const Unit& u, int wr, int wc, int fr, int fq, LAS unsigned char*) const {
;     ...
;                 if (dorope) {
;                     const int pos = row < SEQ ? row : 1024 + ((row - SEQ) & 63);
;                     const f32x4* rt = (const f32x4*)((const float*)(ws + WS_ROPE) + ((size_t)pos * 32 + 4 * fq) * 2);
; #pragma unroll
;                     for (int n = 0; n < 2; ++n) {
;                         const f32x4 t0 = rt[8 * n], t1 = rt[8 * n + 1];
;                         const float cs[4] = {t0[0], t0[2], t1[0], t1[2]}, sn[4] = {t0[1], t0[3], t1[1], t1[3]};
; #pragma unroll
;                         for (int j = 0; j < 4; ++j) { const float x1 = v[0][n][j], x2 = v[1][n][j]; v[0][n][j] = x1 * cs[j] - x2 * sn[j]; v[1][n][j] = x2 * cs[j] + x1 * sn[j]; }
;                     }
;                 }
;                 if (kind == 0 || kind == 3) {
;                     bf16_t* q = (bf16_t*)(ws + (kind == 0 ? WS_QA : WS_QB)) + ((size_t)h * MTOK + row) * 64 + 4 * fq;
; #pragma unroll
;                     for (int bj = 0; bj < 2; ++bj)
; #pragma unroll
;                         for (int n = 0; n < 2; ++n) *(u32x2*)(q + 32 * bj + 16 * n) = pk4(v[bj][n] * QSCALE);
	v_pk_mul_f32 v[184:185], v[92:93], v[140:141] op_sel:[0,0] op_sel_hi:[0,1]
	v_pk_mul_f32 v[182:183], v[92:93], v[142:143] op_sel:[1,0] op_sel_hi:[1,1]
	v_pk_fma_f32 v[140:141], v[84:85], v[140:141], v[184:185] op_sel:[0,1,0] op_sel_hi:[0,0,1] neg_lo:[0,1,0]
	v_pk_fma_f32 v[142:143], v[84:85], v[142:143], v[182:183] op_sel:[1,1,0] op_sel_hi:[1,0,1] neg_lo:[0,1,0]
	v_pk_mul_f32 v[184:185], v[94:95], v[136:137] op_sel:[0,0] op_sel_hi:[0,1]
	v_pk_mul_f32 v[182:183], v[94:95], v[138:139] op_sel:[1,0] op_sel_hi:[1,1]
	v_pk_fma_f32 v[136:137], v[86:87], v[136:137], v[184:185] op_sel:[0,1,0] op_sel_hi:[0,0,1] neg_lo:[0,1,0]
	v_pk_fma_f32 v[138:139], v[86:87], v[138:139], v[182:183] op_sel:[1,1,0] op_sel_hi:[1,0,1] neg_lo:[0,1,0]
	v_pk_mul_f32 v[184:185], v[88:89], v[132:133] op_sel:[0,0] op_sel_hi:[0,1]
	v_pk_mul_f32 v[182:183], v[88:89], v[134:135] op_sel:[1,0] op_sel_hi:[1,1]
	v_pk_fma_f32 v[132:133], v[80:81], v[132:133], v[184:185] op_sel:[0,1,0] op_sel_hi:[0,0,1] neg_lo:[0,1,0]
	v_pk_fma_f32 v[134:135], v[80:81], v[134:135], v[182:183] op_sel:[1,1,0] op_sel_hi:[1,0,1] neg_lo:[0,1,0]
	v_pk_mul_f32 v[184:185], v[90:91], v[128:129] op_sel:[0,0] op_sel_hi:[0,1]
	v_pk_mul_f32 v[182:183], v[90:91], v[130:131] op_sel:[1,0] op_sel_hi:[1,1]
	v_pk_fma_f32 v[128:129], v[82:83], v[128:129], v[184:185] op_sel:[0,1,0] op_sel_hi:[0,0,1] neg_lo:[0,1,0]
	v_pk_fma_f32 v[130:131], v[82:83], v[130:131], v[182:183] op_sel:[1,1,0] op_sel_hi:[1,0,1] neg_lo:[0,1,0]
	v_cvt_pk_bf16_f32 v92, v140, v142
	v_cvt_pk_bf16_f32 v93, v136, v138
	v_cvt_pk_bf16_f32 v84, v141, v143
	v_cvt_pk_bf16_f32 v85, v137, v139
	v_cvt_pk_bf16_f32 v88, v132, v134
	v_cvt_pk_bf16_f32 v89, v128, v130
	v_cvt_pk_bf16_f32 v80, v133, v135
	v_cvt_pk_bf16_f32 v81, v129, v131
	s_add_u32 s50, s46, 0x1800
	s_addc_u32 s51, s47, 0
	global_store_dwordx2 v217, v[92:93], s[50:51]
	global_store_dwordx2 v217, v[88:89], s[50:51] offset:32
	global_store_dwordx2 v217, v[84:85], s[50:51] offset:64
	global_store_dwordx2 v217, v[80:81], s[50:51] offset:96
	s_waitcnt vmcnt(20)
	v_pk_mul_f32 v[184:185], v[76:77], v[244:245] op_sel:[0,0] op_sel_hi:[0,1]
	v_pk_mul_f32 v[182:183], v[76:77], v[246:247] op_sel:[1,0] op_sel_hi:[1,1]
	v_pk_fma_f32 v[244:245], v[68:69], v[244:245], v[184:185] op_sel:[0,1,0] op_sel_hi:[0,0,1] neg_lo:[0,1,0]
	v_pk_fma_f32 v[246:247], v[68:69], v[246:247], v[182:183] op_sel:[1,1,0] op_sel_hi:[1,0,1] neg_lo:[0,1,0]
	v_pk_mul_f32 v[184:185], v[78:79], v[248:249] op_sel:[0,0] op_sel_hi:[0,1]
	v_pk_mul_f32 v[182:183], v[78:79], v[250:251] op_sel:[1,0] op_sel_hi:[1,1]
	v_pk_fma_f32 v[248:249], v[70:71], v[248:249], v[184:185] op_sel:[0,1,0] op_sel_hi:[0,0,1] neg_lo:[0,1,0]
	v_pk_fma_f32 v[250:251], v[70:71], v[250:251], v[182:183] op_sel:[1,1,0] op_sel_hi:[1,0,1] neg_lo:[0,1,0]
	v_pk_mul_f32 v[184:185], v[72:73], v[186:187] op_sel:[0,0] op_sel_hi:[0,1]
	v_pk_mul_f32 v[182:183], v[72:73], v[188:189] op_sel:[1,0] op_sel_hi:[1,1]
	v_pk_fma_f32 v[186:187], v[64:65], v[186:187], v[184:185] op_sel:[0,1,0] op_sel_hi:[0,0,1] neg_lo:[0,1,0]
	v_pk_fma_f32 v[188:189], v[64:65], v[188:189], v[182:183] op_sel:[1,1,0] op_sel_hi:[1,0,1] neg_lo:[0,1,0]
	v_pk_mul_f32 v[184:185], v[74:75], v[220:221] op_sel:[0,0] op_sel_hi:[0,1]
	v_pk_mul_f32 v[182:183], v[74:75], v[222:223] op_sel:[1,0] op_sel_hi:[1,1]
	v_pk_fma_f32 v[220:221], v[66:67], v[220:221], v[184:185] op_sel:[0,1,0] op_sel_hi:[0,0,1] neg_lo:[0,1,0]
	v_pk_fma_f32 v[222:223], v[66:67], v[222:223], v[182:183] op_sel:[1,1,0] op_sel_hi:[1,0,1] neg_lo:[0,1,0]
	v_cvt_pk_bf16_f32 v76, v244, v246
	v_cvt_pk_bf16_f32 v77, v248, v250
	v_cvt_pk_bf16_f32 v68, v245, v247
	v_cvt_pk_bf16_f32 v69, v249, v251
	v_cvt_pk_bf16_f32 v72, v186, v188
	v_cvt_pk_bf16_f32 v73, v220, v222
	v_cvt_pk_bf16_f32 v64, v187, v189
	v_cvt_pk_bf16_f32 v65, v221, v223
	s_add_u32 s50, s46, 0x4000
	s_addc_u32 s51, s47, 0
	global_store_dwordx2 v217, v[76:77], s[50:51]
	global_store_dwordx2 v217, v[72:73], s[50:51] offset:32
	global_store_dwordx2 v217, v[68:69], s[50:51] offset:64
	global_store_dwordx2 v217, v[64:65], s[50:51] offset:96
	s_waitcnt vmcnt(20)
; DI u32x2 pk4(f32x4 v) { u32x2 r; r.x = pk2(v[0], v[1]); r.y = pk2(v[2], v[3]); return r; }
;     DI void operator()(const AccT& acc, const Unit& u, int wr, int wc, int fr, int fq, LAS unsigned char*) const {
;     ...
;                 if (dorope) {
;                     const int pos = row < SEQ ? row : 1024 + ((row - SEQ) & 63);
;                     const f32x4* rt = (const f32x4*)((const float*)(ws + WS_ROPE) + ((size_t)pos * 32 + 4 * fq) * 2);
; #pragma unroll
;                     for (int n = 0; n < 2; ++n) {
;                         const f32x4 t0 = rt[8 * n], t1 = rt[8 * n + 1];
;                         const float cs[4] = {t0[0], t0[2], t1[0], t1[2]}, sn[4] = {t0[1], t0[3], t1[1], t1[3]};
; #pragma unroll
;                         for (int j = 0; j < 4; ++j) { const float x1 = v[0][n][j], x2 = v[1][n][j]; v[0][n][j] = x1 * cs[j] - x2 * sn[j]; v[1][n][j] = x2 * cs[j] + x1 * sn[j]; }
;                     }
;                 }
;                 if (kind == 0 || kind == 3) {
;                     bf16_t* q = (bf16_t*)(ws + (kind == 0 ? WS_QA : WS_QB)) + ((size_t)h * MTOK + row) * 64 + 4 * fq;
; #pragma unroll
;                     for (int bj = 0; bj < 2; ++bj)
; #pragma unroll
;                         for (int n = 0; n < 2; ++n) *(u32x2*)(q + 32 * bj + 16 * n) = pk4(v[bj][n] * QSCALE);
	v_pk_mul_f32 v[184:185], v[44:45], v[124:125] op_sel:[0,0] op_sel_hi:[0,1]
	v_pk_mul_f32 v[182:183], v[44:45], v[126:127] op_sel:[1,0] op_sel_hi:[1,1]
	v_pk_fma_f32 v[124:125], v[36:37], v[124:125], v[184:185] op_sel:[0,1,0] op_sel_hi:[0,0,1] neg_lo:[0,1,0]
	v_pk_fma_f32 v[126:127], v[36:37], v[126:127], v[182:183] op_sel:[1,1,0] op_sel_hi:[1,0,1] neg_lo:[0,1,0]
	v_pk_mul_f32 v[184:185], v[46:47], v[120:121] op_sel:[0,0] op_sel_hi:[0,1]
	v_pk_mul_f32 v[182:183], v[46:47], v[122:123] op_sel:[1,0] op_sel_hi:[1,1]
	v_pk_fma_f32 v[120:121], v[38:39], v[120:121], v[184:185] op_sel:[0,1,0] op_sel_hi:[0,0,1] neg_lo:[0,1,0]
	v_pk_fma_f32 v[122:123], v[38:39], v[122:123], v[182:183] op_sel:[1,1,0] op_sel_hi:[1,0,1] neg_lo:[0,1,0]
	v_pk_mul_f32 v[184:185], v[40:41], v[116:117] op_sel:[0,0] op_sel_hi:[0,1]
	v_pk_mul_f32 v[182:183], v[40:41], v[118:119] op_sel:[1,0] op_sel_hi:[1,1]
	v_pk_fma_f32 v[116:117], v[32:33], v[116:117], v[184:185] op_sel:[0,1,0] op_sel_hi:[0,0,1] neg_lo:[0,1,0]
	v_pk_fma_f32 v[118:119], v[32:33], v[118:119], v[182:183] op_sel:[1,1,0] op_sel_hi:[1,0,1] neg_lo:[0,1,0]
	v_pk_mul_f32 v[184:185], v[42:43], v[112:113] op_sel:[0,0] op_sel_hi:[0,1]
	v_pk_mul_f32 v[182:183], v[42:43], v[114:115] op_sel:[1,0] op_sel_hi:[1,1]
	v_pk_fma_f32 v[112:113], v[34:35], v[112:113], v[184:185] op_sel:[0,1,0] op_sel_hi:[0,0,1] neg_lo:[0,1,0]
	v_pk_fma_f32 v[114:115], v[34:35], v[114:115], v[182:183] op_sel:[1,1,0] op_sel_hi:[1,0,1] neg_lo:[0,1,0]
	v_cvt_pk_bf16_f32 v44, v124, v126
	v_cvt_pk_bf16_f32 v45, v120, v122
	v_cvt_pk_bf16_f32 v36, v125, v127
	v_cvt_pk_bf16_f32 v37, v121, v123
	v_cvt_pk_bf16_f32 v40, v116, v118
	v_cvt_pk_bf16_f32 v41, v112, v114
	v_cvt_pk_bf16_f32 v32, v117, v119
	v_cvt_pk_bf16_f32 v33, v113, v115
	s_add_u32 s50, s46, 0x4800
	s_addc_u32 s51, s47, 0
	global_store_dwordx2 v217, v[44:45], s[50:51]
	global_store_dwordx2 v217, v[40:41], s[50:51] offset:32
	global_store_dwordx2 v217, v[36:37], s[50:51] offset:64
	global_store_dwordx2 v217, v[32:33], s[50:51] offset:96
	s_waitcnt vmcnt(16)
	v_pk_mul_f32 v[184:185], v[28:29], v[228:229] op_sel:[0,0] op_sel_hi:[0,1]
	v_pk_mul_f32 v[182:183], v[28:29], v[230:231] op_sel:[1,0] op_sel_hi:[1,1]
	v_pk_fma_f32 v[228:229], v[20:21], v[228:229], v[184:185] op_sel:[0,1,0] op_sel_hi:[0,0,1] neg_lo:[0,1,0]
	v_pk_fma_f32 v[230:231], v[20:21], v[230:231], v[182:183] op_sel:[1,1,0] op_sel_hi:[1,0,1] neg_lo:[0,1,0]
	v_pk_mul_f32 v[184:185], v[30:31], v[232:233] op_sel:[0,0] op_sel_hi:[0,1]
	v_pk_mul_f32 v[182:183], v[30:31], v[234:235] op_sel:[1,0] op_sel_hi:[1,1]
	v_pk_fma_f32 v[232:233], v[22:23], v[232:233], v[184:185] op_sel:[0,1,0] op_sel_hi:[0,0,1] neg_lo:[0,1,0]
	v_pk_fma_f32 v[234:235], v[22:23], v[234:235], v[182:183] op_sel:[1,1,0] op_sel_hi:[1,0,1] neg_lo:[0,1,0]
	v_pk_mul_f32 v[184:185], v[24:25], v[236:237] op_sel:[0,0] op_sel_hi:[0,1]
	v_pk_mul_f32 v[182:183], v[24:25], v[238:239] op_sel:[1,0] op_sel_hi:[1,1]
	v_pk_fma_f32 v[236:237], v[16:17], v[236:237], v[184:185] op_sel:[0,1,0] op_sel_hi:[0,0,1] neg_lo:[0,1,0]
	v_pk_fma_f32 v[238:239], v[16:17], v[238:239], v[182:183] op_sel:[1,1,0] op_sel_hi:[1,0,1] neg_lo:[0,1,0]
	v_pk_mul_f32 v[184:185], v[26:27], v[240:241] op_sel:[0,0] op_sel_hi:[0,1]
	v_pk_mul_f32 v[182:183], v[26:27], v[242:243] op_sel:[1,0] op_sel_hi:[1,1]
	v_pk_fma_f32 v[240:241], v[18:19], v[240:241], v[184:185] op_sel:[0,1,0] op_sel_hi:[0,0,1] neg_lo:[0,1,0]
	v_pk_fma_f32 v[242:243], v[18:19], v[242:243], v[182:183] op_sel:[1,1,0] op_sel_hi:[1,0,1] neg_lo:[0,1,0]
	v_cvt_pk_bf16_f32 v28, v228, v230
	v_cvt_pk_bf16_f32 v29, v232, v234
	v_cvt_pk_bf16_f32 v20, v229, v231
	v_cvt_pk_bf16_f32 v21, v233, v235
	v_cvt_pk_bf16_f32 v24, v236, v238
	v_cvt_pk_bf16_f32 v25, v240, v242
	v_cvt_pk_bf16_f32 v16, v237, v239
	v_cvt_pk_bf16_f32 v17, v241, v243
	s_add_u32 s50, s46, 0x5000
	s_addc_u32 s51, s47, 0
	global_store_dwordx2 v217, v[28:29], s[50:51]
	global_store_dwordx2 v217, v[24:25], s[50:51] offset:32
	global_store_dwordx2 v217, v[20:21], s[50:51] offset:64
	global_store_dwordx2 v217, v[16:17], s[50:51] offset:96
	s_waitcnt vmcnt(16)
	v_pk_mul_f32 v[184:185], v[12:13], v[108:109] op_sel:[0,0] op_sel_hi:[0,1]
	v_pk_mul_f32 v[182:183], v[12:13], v[110:111] op_sel:[1,0] op_sel_hi:[1,1]
	v_pk_fma_f32 v[108:109], v[4:5], v[108:109], v[184:185] op_sel:[0,1,0] op_sel_hi:[0,0,1] neg_lo:[0,1,0]
	v_pk_fma_f32 v[110:111], v[4:5], v[110:111], v[182:183] op_sel:[1,1,0] op_sel_hi:[1,0,1] neg_lo:[0,1,0]
	v_pk_mul_f32 v[184:185], v[14:15], v[104:105] op_sel:[0,0] op_sel_hi:[0,1]
	v_pk_mul_f32 v[182:183], v[14:15], v[106:107] op_sel:[1,0] op_sel_hi:[1,1]
	v_pk_fma_f32 v[104:105], v[6:7], v[104:105], v[184:185] op_sel:[0,1,0] op_sel_hi:[0,0,1] neg_lo:[0,1,0]
	v_pk_fma_f32 v[106:107], v[6:7], v[106:107], v[182:183] op_sel:[1,1,0] op_sel_hi:[1,0,1] neg_lo:[0,1,0]
	v_pk_mul_f32 v[184:185], v[8:9], v[100:101] op_sel:[0,0] op_sel_hi:[0,1]
	v_pk_mul_f32 v[182:183], v[8:9], v[102:103] op_sel:[1,0] op_sel_hi:[1,1]
	v_pk_fma_f32 v[100:101], v[0:1], v[100:101], v[184:185] op_sel:[0,1,0] op_sel_hi:[0,0,1] neg_lo:[0,1,0]
	v_pk_fma_f32 v[102:103], v[0:1], v[102:103], v[182:183] op_sel:[1,1,0] op_sel_hi:[1,0,1] neg_lo:[0,1,0]
	v_pk_mul_f32 v[184:185], v[10:11], v[96:97] op_sel:[0,0] op_sel_hi:[0,1]
	v_pk_mul_f32 v[182:183], v[10:11], v[98:99] op_sel:[1,0] op_sel_hi:[1,1]
	v_pk_fma_f32 v[96:97], v[2:3], v[96:97], v[184:185] op_sel:[0,1,0] op_sel_hi:[0,0,1] neg_lo:[0,1,0]
	v_pk_fma_f32 v[98:99], v[2:3], v[98:99], v[182:183] op_sel:[1,1,0] op_sel_hi:[1,0,1] neg_lo:[0,1,0]
	v_cvt_pk_bf16_f32 v12, v108, v110
	v_cvt_pk_bf16_f32 v13, v104, v106
	v_cvt_pk_bf16_f32 v4, v109, v111
	v_cvt_pk_bf16_f32 v5, v105, v107
	v_cvt_pk_bf16_f32 v8, v100, v102
	v_cvt_pk_bf16_f32 v9, v96, v98
	v_cvt_pk_bf16_f32 v0, v101, v103
	v_cvt_pk_bf16_f32 v1, v97, v99
	s_add_u32 s50, s46, 0x5800
	s_addc_u32 s51, s47, 0
	global_store_dwordx2 v217, v[12:13], s[50:51]
	global_store_dwordx2 v217, v[8:9], s[50:51] offset:32
	global_store_dwordx2 v217, v[4:5], s[50:51] offset:64
	global_store_dwordx2 v217, v[0:1], s[50:51] offset:96
	s_branch .LBB0_505
